# baseline (speedup 1.0000x reference)
; __device__ __forceinline__ bf16_t f2bf(float v) { return (bf16_t)(cvt_pk_bf16(v, 0.f) & 0xffffu); }
; __device__ __forceinline__ float bflo(unsigned w) { return __uint_as_float(w << 16); }
; __device__ __forceinline__ float bfhi(unsigned w) { return __uint_as_float(w & 0xffff0000u); }
; __device__ __forceinline__ void gmlp_item(KP P, int ch, int h, unsigned char* lds) {
;     ...
;     const int t = threadIdx.x, w = t >> 6, lane = t & 63, r0 = ch * 128;
;     bf16_t uu16[8][4]; float bsv[4];
; #pragma unroll
;     for (int reg = 0; reg < 4; ++reg) {
;         const int tt = 16 * w + (lane >> 4) * 4 + reg;
;         bsv[reg] = bs[tt * 8 + h];
; #pragma unroll
;         for (int db = 0; db < 8; ++db) uu16[db][reg] = proj[(size_t)(r0 + tt) * 4096 + 1024 + h * 128 + db * 16 + (lane & 15)];
;     }
;     {
;         const int d0 = (t & 15) * 8;
;         float gg[8], bb[8];
; #pragma unroll
;         for (int j = 0; j < 8; ++j) { gg[j] = lng[h * 128 + d0 + j]; bb[j] = lnb[h * 128 + d0 + j]; }
; #pragma unroll
;         for (int i = 0; i < 4; ++i) {
;             const int s = (t >> 4) + 32 * i;
;             const u32x4 x = *(const u32x4*)(proj + (size_t)(r0 + s) * 4096 + 2048 + h * 128 + d0);
;             const f32x2 st = stats[s];
; #pragma unroll
;             for (int j = 0; j < 4; ++j) {
;                 T[(d0 + 2 * j) * 136 + s] = f2bf((bflo(x[j]) - st.x) * st.y * gg[2 * j] + bb[2 * j]);
;                 T[(d0 + 2 * j + 1) * 136 + s] = f2bf((bfhi(x[j]) - st.x) * st.y * gg[2 * j + 1] + bb[2 * j + 1]);
;             }
;         }
;     }
.Lmy_deq_skip1:
	s_or_b64 exec, exec, s[100:101]
	v_cmp_gt_i32_e32 vcc, s56, v0
	s_and_saveexec_b64 s[48:49], vcc
	s_cbranch_execz .LBB0_1080
	v_cmp_lt_i32_e32 vcc, 47, v0
	s_and_saveexec_b64 s[12:13], vcc
	s_xor_b64 s[50:51], exec, s[12:13]
	s_cbranch_execz .LBB0_1092
	v_cmp_lt_u32_e32 vcc, s57, v0
	s_and_saveexec_b64 s[12:13], vcc
	s_xor_b64 s[52:53], exec, s[12:13]
	s_cbranch_execz .LBB0_1089
	v_and_b32_e32 v46, 7, v0
	v_lshlrev_b32_e32 v0, 4, v0
	v_and_b32_e32 v0, 0x7fffff80, v0
	v_lshlrev_b32_e32 v51, 7, v46
	v_add_lshl_u32 v236, v51, v141, 8
	v_mov_b32_e32 v237, v103
	v_lshl_add_u64 v[236:237], v[104:105], 0, v[236:237]
	global_load_dwordx4 v[240:243], v[236:237], off
	global_load_dwordx4 v[244:247], v[236:237], off offset:64
	global_load_dwordx4 v[248:251], v[236:237], off offset:128
	global_load_dwordx4 v[252:255], v[236:237], off offset:192
	v_add_u32_e32 v102, 0xffffdd00, v0
	v_or_b32_e32 v0, v51, v100
	v_lshlrev_b32_e32 v12, 2, v0
	v_or_b32_e32 v0, v102, v135
	v_lshlrev_b32_e32 v0, 13, v0
	v_mov_b32_e32 v1, v103
	v_lshl_add_u64 v[0:1], s[38:39], 0, v[0:1]
	v_lshlrev_b32_e32 v20, 8, v46
	v_mov_b32_e32 v21, v103
	s_load_dwordx4 s[12:15], s[30:31], 0x90
	s_load_dwordx2 s[54:55], s[30:31], 0xa8
	v_lshl_add_u64 v[0:1], v[0:1], 0, v[20:21]
	v_lshlrev_b32_e32 v22, 1, v100
	v_mov_b32_e32 v23, v103
	v_lshl_add_u64 v[0:1], v[0:1], 0, v[22:23]
	v_add_co_u32_e32 v0, vcc, s58, v0
	v_lshl_add_u64 v[24:25], v[102:103], 3, v[114:115]
	s_nop 0
	v_addc_co_u32_e32 v1, vcc, 0, v1, vcc
	global_load_dwordx4 v[16:19], v[0:1], off
	global_load_dwordx2 v[26:27], v[24:25], off
	v_or_b32_e32 v218, v102, v139
	v_lshlrev_b32_e32 v218, 13, v218
	v_mov_b32_e32 v219, v103
	v_lshl_add_u64 v[218:219], s[38:39], 0, v[218:219]
	v_lshl_add_u64 v[218:219], v[218:219], 0, v[20:21]
	v_lshl_add_u64 v[218:219], v[218:219], 0, v[22:23]
	v_add_co_u32_e32 v218, vcc, s58, v218
	s_nop 1
	v_addc_co_u32_e32 v219, vcc, 0, v219, vcc
	global_load_dwordx4 v[212:215], v[218:219], off
	global_load_dwordx2 v[216:217], v[24:25], off offset:512
	s_waitcnt lgkmcnt(0)
	global_load_dwordx4 v[0:3], v12, s[12:13]
	global_load_dwordx4 v[4:7], v12, s[14:15]
	v_or_b32_e32 v8, v46, v128
	v_or_b32_e32 v9, v46, v130
	v_or_b32_e32 v10, v46, v132
	v_or_b32_e32 v11, v51, v166
	v_lshlrev_b32_e32 v30, 2, v8
	v_lshlrev_b32_e32 v31, 2, v9
	v_lshlrev_b32_e32 v33, 2, v10
	v_lshlrev_b32_e32 v29, 1, v11
	global_load_dwordx4 v[8:11], v12, s[12:13] offset:16
	s_nop 0
	global_load_dwordx4 v[12:15], v12, s[14:15] offset:16
	v_add_u32_e32 v28, v102, v101
	v_add_u32_e32 v32, v102, v129
	v_add_u32_e32 v36, v102, v131
	v_add_u32_e32 v38, v102, v133
	v_lshl_or_b32 v40, v28, 13, v29
	v_lshl_or_b32 v43, v32, 13, v29
	v_lshl_or_b32 v44, v36, 13, v29
	v_lshl_or_b32 v62, v38, 13, v29
	global_load_dwordx2 v[28:29], v[24:25], off offset:256
	global_load_dword v32, v30, s[54:55]
	s_nop 0
	global_load_dword v31, v31, s[54:55]
	s_nop 0
	global_load_dword v30, v33, s[54:55]
	v_or_b32_e32 v39, v102, v138
	v_mov_b32_e32 v35, v103
	v_mov_b32_e32 v37, v103
	v_or_b32_e32 v34, v46, v134
	v_lshlrev_b32_e32 v36, 13, v39
	v_lshl_add_u64 v[60:61], v[34:35], 2, s[54:55]
	v_lshl_add_u64 v[34:35], s[38:39], 0, v[36:37]
	v_lshl_add_u64 v[34:35], v[34:35], 0, v[20:21]
	v_lshl_add_u64 v[34:35], v[34:35], 0, v[22:23]
	v_add_co_u32_e32 v34, vcc, s58, v34
	global_load_ushort v66, v40, s[38:39] offset:2048
	global_load_ushort v67, v40, s[38:39] offset:2080
	global_load_ushort v68, v40, s[38:39] offset:2112
	global_load_ushort v52, v40, s[38:39] offset:2144
	global_load_ushort v49, v40, s[38:39] offset:2176
	global_load_ushort v42, v40, s[38:39] offset:2208
	global_load_ushort v38, v40, s[38:39] offset:2240
	global_load_ushort v33, v40, s[38:39] offset:2272
	v_addc_co_u32_e32 v35, vcc, 0, v35, vcc
	global_load_dwordx4 v[56:59], v[34:35], off
	global_load_ushort v69, v43, s[38:39] offset:2048
	global_load_ushort v70, v43, s[38:39] offset:2080
	global_load_ushort v71, v43, s[38:39] offset:2112
	global_load_ushort v55, v43, s[38:39] offset:2144
	global_load_ushort v50, v43, s[38:39] offset:2176
	global_load_ushort v45, v43, s[38:39] offset:2208
	global_load_ushort v41, v43, s[38:39] offset:2240
	global_load_ushort v35, v43, s[38:39] offset:2272
	global_load_ushort v72, v44, s[38:39] offset:2048
	global_load_ushort v73, v44, s[38:39] offset:2080
	global_load_ushort v74, v44, s[38:39] offset:2112
	global_load_ushort v53, v44, s[38:39] offset:2144
	global_load_ushort v47, v44, s[38:39] offset:2176
	global_load_ushort v43, v44, s[38:39] offset:2208
	global_load_ushort v39, v44, s[38:39] offset:2240
	global_load_ushort v36, v44, s[38:39] offset:2272
	global_load_dword v34, v[60:61], off
	s_waitcnt vmcnt(35)
	v_lshlrev_b32_e32 v37, 16, v16
	v_and_b32_e32 v16, 0xffff0000, v16
	s_waitcnt vmcnt(34)
	v_sub_f32_e32 v16, v16, v26
	v_sub_f32_e32 v37, v37, v26
	v_mul_f32_e32 v16, v27, v16
	v_mul_f32_e32 v37, v27, v37
	s_waitcnt vmcnt(32)
	v_fma_f32 v16, v1, v16, v5
	v_fma_f32 v37, v0, v37, v4
	v_cvt_pk_bf16_f32 v16, v16, s0
	v_cvt_pk_bf16_f32 v60, v37, s0
	global_load_ushort v75, v62, s[38:39] offset:2048
	global_load_ushort v76, v62, s[38:39] offset:2080
	global_load_ushort v77, v62, s[38:39] offset:2112
	global_load_ushort v54, v62, s[38:39] offset:2144
	global_load_ushort v48, v62, s[38:39] offset:2176
	global_load_ushort v44, v62, s[38:39] offset:2208
	global_load_ushort v40, v62, s[38:39] offset:2240
	global_load_ushort v37, v62, s[38:39] offset:2272
	ds_write_b16 v137, v16 offset:1296
	v_lshlrev_b32_e32 v16, 16, v17
	v_sub_f32_e32 v16, v16, v26
	v_mul_f32_e32 v16, v27, v16
	v_fma_f32 v16, v2, v16, v6
	v_cvt_pk_bf16_f32 v16, v16, s0
	ds_write_b16 v136, v16 offset:1568
	v_and_b32_e32 v16, 0xffff0000, v17
	v_sub_f32_e32 v16, v16, v26
	v_mul_f32_e32 v16, v27, v16
	v_fma_f32 v16, v3, v16, v7
	v_cvt_pk_bf16_f32 v16, v16, s0
	ds_write_b16 v137, v16 offset:1840
	v_lshlrev_b32_e32 v16, 16, v18
	v_sub_f32_e32 v16, v16, v26
	v_mul_f32_e32 v16, v27, v16
	s_waitcnt vmcnt(38)
; __device__ __forceinline__ bf16_t f2bf(float v) { return (bf16_t)(cvt_pk_bf16(v, 0.f) & 0xffffu); }
; __device__ __forceinline__ float bflo(unsigned w) { return __uint_as_float(w << 16); }
; __device__ __forceinline__ float bfhi(unsigned w) { return __uint_as_float(w & 0xffff0000u); }
; __device__ __forceinline__ void gmlp_item(KP P, int ch, int h, unsigned char* lds) {
;     ...
;     {
;         const int d0 = (t & 15) * 8;
;         float gg[8], bb[8];
; #pragma unroll
;         for (int j = 0; j < 8; ++j) { gg[j] = lng[h * 128 + d0 + j]; bb[j] = lnb[h * 128 + d0 + j]; }
; #pragma unroll
;         for (int i = 0; i < 4; ++i) {
;             const int s = (t >> 4) + 32 * i;
;             const u32x4 x = *(const u32x4*)(proj + (size_t)(r0 + s) * 4096 + 2048 + h * 128 + d0);
;             const f32x2 st = stats[s];
; #pragma unroll
;             for (int j = 0; j < 4; ++j) {
;                 T[(d0 + 2 * j) * 136 + s] = f2bf((bflo(x[j]) - st.x) * st.y * gg[2 * j] + bb[2 * j]);
;                 T[(d0 + 2 * j + 1) * 136 + s] = f2bf((bfhi(x[j]) - st.x) * st.y * gg[2 * j + 1] + bb[2 * j + 1]);
;             }
;         }
;     }
;     __syncthreads();
	v_fma_f32 v16, v8, v16, v12
	v_cvt_pk_bf16_f32 v78, v16, s0
	v_or_b32_e32 v16, v102, v139
	v_lshlrev_b32_e32 v16, 13, v16
	v_mov_b32_e32 v17, v103
	v_lshl_add_u64 v[16:17], s[38:39], 0, v[16:17]
	v_lshl_add_u64 v[16:17], v[16:17], 0, v[20:21]
	v_lshl_add_u64 v[16:17], v[16:17], 0, v[22:23]
	v_add_co_u32_e32 v16, vcc, s58, v16
	ds_write_b16 v136, v60 offset:1024
	s_nop 0
	v_addc_co_u32_e32 v17, vcc, 0, v17, vcc
	v_and_b32_e32 v16, 0xffff0000, v18
	v_sub_f32_e32 v16, v16, v26
	v_mul_f32_e32 v16, v27, v16
	v_fma_f32 v16, v9, v16, v13
	v_cvt_pk_bf16_f32 v16, v16, s0
	ds_write_b16 v137, v16 offset:2384
	v_lshlrev_b32_e32 v16, 16, v19
	v_sub_f32_e32 v16, v16, v26
	v_mul_f32_e32 v16, v27, v16
	v_fma_f32 v16, v10, v16, v14
	v_cvt_pk_bf16_f32 v16, v16, s0
	ds_write_b16 v136, v16 offset:2656
	v_and_b32_e32 v16, 0xffff0000, v19
	v_sub_f32_e32 v16, v16, v26
	v_mul_f32_e32 v16, v27, v16
	v_fma_f32 v16, v11, v16, v15
	v_cvt_pk_bf16_f32 v16, v16, s0
	ds_write_b16 v137, v16 offset:2928
	s_waitcnt vmcnt(25)
	v_lshlrev_b32_e32 v16, 16, v56
	v_sub_f32_e32 v16, v16, v28
	v_mul_f32_e32 v16, v29, v16
	v_fma_f32 v16, v0, v16, v4
	v_cvt_pk_bf16_f32 v16, v16, s0
	ds_write_b16 v136, v16 offset:1088
	v_and_b32_e32 v16, 0xffff0000, v56
	v_sub_f32_e32 v16, v16, v28
	v_mul_f32_e32 v16, v29, v16
	v_fma_f32 v16, v1, v16, v5
	v_cvt_pk_bf16_f32 v16, v16, s0
	ds_write_b16 v137, v16 offset:1360
	v_lshlrev_b32_e32 v16, 16, v57
	v_sub_f32_e32 v16, v16, v28
	v_mul_f32_e32 v16, v29, v16
	v_fma_f32 v16, v2, v16, v6
	v_cvt_pk_bf16_f32 v26, v16, s0
	v_add_lshl_u32 v16, v102, v140, 13
	v_mov_b32_e32 v17, v103
	v_lshl_add_u64 v[16:17], s[38:39], 0, v[16:17]
	v_lshl_add_u64 v[16:17], v[16:17], 0, v[20:21]
	v_lshl_add_u64 v[16:17], v[16:17], 0, v[22:23]
	v_add_co_u32_e32 v16, vcc, s58, v16
	global_load_dwordx2 v[24:25], v[24:25], off offset:768
	s_nop 0
	v_addc_co_u32_e32 v17, vcc, 0, v17, vcc
	global_load_dwordx4 v[16:19], v[16:17], off
	v_and_b32_e32 v20, 0xffff0000, v57
	v_sub_f32_e32 v20, v20, v28
	v_mul_f32_e32 v20, v29, v20
	v_fma_f32 v20, v3, v20, v7
	v_cvt_pk_bf16_f32 v20, v20, s0
	ds_write_b16 v137, v20 offset:1904
	v_lshlrev_b32_e32 v20, 16, v58
	v_sub_f32_e32 v20, v20, v28
	v_mul_f32_e32 v20, v29, v20
	v_fma_f32 v20, v8, v20, v12
	v_cvt_pk_bf16_f32 v20, v20, s0
	ds_write_b16 v136, v20 offset:2176
	v_and_b32_e32 v20, 0xffff0000, v58
	v_sub_f32_e32 v20, v20, v28
	v_mul_f32_e32 v20, v29, v20
	v_fma_f32 v20, v9, v20, v13
	v_cvt_pk_bf16_f32 v20, v20, s0
	ds_write_b16 v137, v20 offset:2448
	v_lshlrev_b32_e32 v20, 16, v59
	v_sub_f32_e32 v20, v20, v28
	v_mul_f32_e32 v20, v29, v20
	v_fma_f32 v20, v10, v20, v14
	v_cvt_pk_bf16_f32 v20, v20, s0
	ds_write_b16 v136, v20 offset:2720
	v_and_b32_e32 v20, 0xffff0000, v59
	v_sub_f32_e32 v20, v20, v28
	v_mul_f32_e32 v20, v29, v20
	v_fma_f32 v20, v11, v20, v15
	v_cvt_pk_bf16_f32 v20, v20, s0
	ds_write_b16 v137, v20 offset:2992
	ds_write_b16 v136, v78 offset:2112
	ds_write_b16 v136, v26 offset:1632
	s_waitcnt vmcnt(3)
	v_lshlrev_b32_e32 v20, 16, v212
	s_waitcnt vmcnt(2)
	v_sub_f32_e32 v20, v20, v216
	v_mul_f32_e32 v20, v217, v20
	v_fma_f32 v20, v0, v20, v4
	v_cvt_pk_bf16_f32 v20, v20, s0
	ds_write_b16 v136, v20 offset:1152
	v_and_b32_e32 v20, 0xffff0000, v212
	v_sub_f32_e32 v20, v20, v216
	v_mul_f32_e32 v20, v217, v20
	v_fma_f32 v20, v1, v20, v5
	v_cvt_pk_bf16_f32 v20, v20, s0
	ds_write_b16 v137, v20 offset:1424
	v_lshlrev_b32_e32 v20, 16, v213
	v_sub_f32_e32 v20, v20, v216
	v_mul_f32_e32 v20, v217, v20
	v_fma_f32 v20, v2, v20, v6
	v_cvt_pk_bf16_f32 v20, v20, s0
	ds_write_b16 v136, v20 offset:1696
	v_and_b32_e32 v20, 0xffff0000, v213
	v_sub_f32_e32 v20, v20, v216
	v_mul_f32_e32 v20, v217, v20
	v_fma_f32 v20, v3, v20, v7
	v_cvt_pk_bf16_f32 v20, v20, s0
	ds_write_b16 v137, v20 offset:1968
	v_lshlrev_b32_e32 v20, 16, v214
	v_sub_f32_e32 v20, v20, v216
	v_mul_f32_e32 v20, v217, v20
	v_fma_f32 v20, v8, v20, v12
	v_cvt_pk_bf16_f32 v20, v20, s0
	ds_write_b16 v136, v20 offset:2240
	v_and_b32_e32 v20, 0xffff0000, v214
	v_sub_f32_e32 v20, v20, v216
	v_mul_f32_e32 v20, v217, v20
	v_fma_f32 v20, v9, v20, v13
	v_cvt_pk_bf16_f32 v20, v20, s0
	ds_write_b16 v137, v20 offset:2512
	v_lshlrev_b32_e32 v20, 16, v215
	v_sub_f32_e32 v20, v20, v216
	v_mul_f32_e32 v20, v217, v20
	v_fma_f32 v20, v10, v20, v14
	v_cvt_pk_bf16_f32 v20, v20, s0
	ds_write_b16 v136, v20 offset:2784
	v_and_b32_e32 v20, 0xffff0000, v215
	v_sub_f32_e32 v20, v20, v216
	v_mul_f32_e32 v20, v217, v20
	v_fma_f32 v20, v11, v20, v15
	v_cvt_pk_bf16_f32 v20, v20, s0
	ds_write_b16 v137, v20 offset:3056
	s_waitcnt vmcnt(0)
	v_lshlrev_b32_e32 v20, 16, v16
	v_sub_f32_e32 v20, v20, v24
	v_mul_f32_e32 v20, v25, v20
	v_fma_f32 v0, v0, v20, v4
	v_cvt_pk_bf16_f32 v0, v0, s0
	ds_write_b16 v136, v0 offset:1216
	v_and_b32_e32 v0, 0xffff0000, v16
	v_sub_f32_e32 v0, v0, v24
	v_mul_f32_e32 v0, v25, v0
	v_fma_f32 v0, v1, v0, v5
	v_cvt_pk_bf16_f32 v0, v0, s0
	ds_write_b16 v137, v0 offset:1488
	v_lshlrev_b32_e32 v0, 16, v17
	v_sub_f32_e32 v0, v0, v24
	v_mul_f32_e32 v0, v25, v0
	v_fma_f32 v0, v2, v0, v6
	v_cvt_pk_bf16_f32 v0, v0, s0
	ds_write_b16 v136, v0 offset:1760
	v_and_b32_e32 v0, 0xffff0000, v17
	v_sub_f32_e32 v0, v0, v24
	v_mul_f32_e32 v0, v25, v0
	v_fmac_f32_e32 v7, v3, v0
	v_cvt_pk_bf16_f32 v0, v7, s0
	ds_write_b16 v137, v0 offset:2032
	v_lshlrev_b32_e32 v0, 16, v18
	v_sub_f32_e32 v0, v0, v24
	v_mul_f32_e32 v0, v25, v0
	v_fma_f32 v0, v8, v0, v12
	v_cvt_pk_bf16_f32 v0, v0, s0
	ds_write_b16 v136, v0 offset:2304
	v_and_b32_e32 v0, 0xffff0000, v18
	v_sub_f32_e32 v0, v0, v24
	v_mul_f32_e32 v0, v25, v0
	v_fma_f32 v0, v9, v0, v13
	v_cvt_pk_bf16_f32 v0, v0, s0
	ds_write_b16 v137, v0 offset:2576
	v_lshlrev_b32_e32 v0, 16, v19
	v_sub_f32_e32 v0, v0, v24
	v_mul_f32_e32 v0, v25, v0
	v_fma_f32 v0, v10, v0, v14
	v_cvt_pk_bf16_f32 v0, v0, s0
	ds_write_b16 v136, v0 offset:2848
	v_and_b32_e32 v0, 0xffff0000, v19
	v_sub_f32_e32 v0, v0, v24
	v_mul_f32_e32 v0, v25, v0
	v_fmac_f32_e32 v15, v11, v0
	v_cvt_pk_bf16_f32 v0, v15, s0
	ds_write_b16 v137, v0 offset:3120
	v_add_lshl_u32 v0, v51, v141, 8
	v_mov_b32_e32 v1, v103
	v_lshl_add_u64 v[24:25], v[104:105], 0, v[0:1]
	s_waitcnt lgkmcnt(0)
	s_barrier
; __device__ __forceinline__ bf16_t f2bf(float v) { return (bf16_t)(cvt_pk_bf16(v, 0.f) & 0xffffu); }
; __device__ __forceinline__ float bf2f(bf16_t b) { return __uint_as_float(((unsigned)b) << 16); }
; __device__ __forceinline__ size_t tl(int r, int c, int K) { return ((size_t)(r >> 8) * (size_t)(K >> 6) + (size_t)(c >> 6)) * 16384 + (size_t)((r & 255) << 6) + (size_t)(c & 63); }
; #define MFMA16(a, b, c) __builtin_amdgcn_mfma_f32_16x16x32_bf16((a), (b), (c), 0, 0, 0)
; __device__ __forceinline__ void gmlp_item(KP P, int ch, int h, unsigned char* lds) {
;     ...
;         bf16x8 Wa[4];
; #pragma unroll
;         for (int ks = 0; ks < 4; ++ks) Wa[ks] = *(const bf16x8*)(Wsb + ((size_t)h * 128 + 16 * w + l15) * 128 + ks * 32 + 8 * q);
; #pragma unroll
;         for (int db = 0; db < 8; ++db) {
;             f32x4 acc = (f32x4){0.f, 0.f, 0.f, 0.f};
; #pragma unroll
;             for (int ks = 0; ks < 4; ++ks) acc = MFMA16(Wa[ks], *(const bf16x8*)(T + (db * 16 + l15) * 136 + ks * 32 + 8 * q), acc);
; #pragma unroll
;             for (int reg = 0; reg < 4; ++reg) {
;                 const int tt = 16 * w + q * 4 + reg, c = h * 128 + db * 16 + l15;
;                 gm[tl(r0 + tt, c, 1024)] = f2bf(bf2f(uu16[db][reg]) * (acc[reg] + bsv[reg]));
;             }
;         }
	ds_read_b128 v[8:11], v152 offset:1024
	ds_read_b128 v[16:19], v152 offset:1088
	v_mov_b32_e32 v29, v103
	v_lshlrev_b32_e32 v60, 1, v166
	v_mov_b32_e32 v61, v103
	s_waitcnt vmcnt(2) lgkmcnt(1)
	v_mfma_f32_16x16x32_bf16 v[20:23], v[240:243], v[8:11], 0
	s_waitcnt vmcnt(2) lgkmcnt(0)
	v_mfma_f32_16x16x32_bf16 v[16:19], v[244:247], v[16:19], v[20:23]
	s_nop 4
	ds_read_b128 v[20:23], v152 offset:1152
	ds_read_b128 v[24:27], v152 offset:1216
	ds_read_b128 v[56:59], v152 offset:5504
	s_waitcnt vmcnt(1) lgkmcnt(2)
	v_mfma_f32_16x16x32_bf16 v[16:19], v[248:251], v[20:23], v[16:19]
	v_add_u32_e32 v22, v142, v102
	v_lshlrev_b32_e32 v20, 16, v66
	s_waitcnt vmcnt(0) lgkmcnt(1)
	v_mfma_f32_16x16x32_bf16 v[16:19], v[252:255], v[24:27], v[16:19]
	ds_read_b128 v[24:27], v152 offset:5440
	s_nop 6
	v_add_f32_e32 v16, v32, v16
	v_mul_f32_e32 v16, v16, v20
	v_lshlrev_b32_e32 v20, 11, v22
	v_and_b32_e32 v20, 0x3f80000, v20
	v_lshl_or_b32 v102, v46, 16, v20
	v_lshlrev_b32_e32 v22, 7, v22
	v_lshl_add_u64 v[20:21], s[40:41], 0, v[102:103]
	v_and_b32_e32 v28, 0x7e00, v22
	v_lshl_add_u64 v[20:21], v[20:21], 0, v[28:29]
	v_lshl_add_u64 v[62:63], v[20:21], 0, v[60:61]
	ds_read_b128 v[20:23], v152 offset:5376
	v_cvt_pk_bf16_f32 v16, v16, s0
	s_waitcnt lgkmcnt(0)
	v_mfma_f32_16x16x32_bf16 v[20:23], v[240:243], v[20:23], 0
	global_store_short v[62:63], v16, off
	v_lshlrev_b32_e32 v16, 16, v69
	v_add_f32_e32 v17, v31, v17
	v_mul_f32_e32 v16, v17, v16
	v_cvt_pk_bf16_f32 v16, v16, s0
	global_store_short v[62:63], v16, off offset:128
	v_lshlrev_b32_e32 v16, 16, v72
	v_add_f32_e32 v17, v30, v18
	v_mfma_f32_16x16x32_bf16 v[20:23], v[244:247], v[24:27], v[20:23]
	v_mul_f32_e32 v16, v17, v16
	v_cvt_pk_bf16_f32 v16, v16, s0
	global_store_short v[62:63], v16, off offset:256
	v_add_f32_e32 v25, v34, v19
	ds_read_b128 v[16:19], v152 offset:5568
	v_mfma_f32_16x16x32_bf16 v[20:23], v[248:251], v[56:59], v[20:23]
	v_lshlrev_b32_e32 v24, 16, v75
	v_mul_f32_e32 v24, v25, v24
	v_cvt_pk_bf16_f32 v24, v24, s0
	s_waitcnt lgkmcnt(0)
	v_mfma_f32_16x16x32_bf16 v[16:19], v[252:255], v[16:19], v[20:23]
	global_store_short v[62:63], v24, off offset:384
	ds_read_b128 v[24:27], v152 offset:9792
	ds_read_b128 v[56:59], v152 offset:9856
	v_lshlrev_b32_e32 v20, 16, v67
	v_or_b32_e32 v102, 0x8000, v102
	s_nop 2
	v_add_f32_e32 v16, v32, v16
	v_mul_f32_e32 v16, v16, v20
	ds_read_b128 v[20:23], v152 offset:9728
	v_cvt_pk_bf16_f32 v16, v16, s0
	s_waitcnt lgkmcnt(0)
	v_mfma_f32_16x16x32_bf16 v[20:23], v[240:243], v[20:23], 0
	global_store_short v[62:63], v16, off offset:32
	v_lshlrev_b32_e32 v16, 16, v70
	v_add_f32_e32 v17, v31, v17
	v_mul_f32_e32 v16, v17, v16
	v_cvt_pk_bf16_f32 v16, v16, s0
	global_store_short v[62:63], v16, off offset:160
	v_lshlrev_b32_e32 v16, 16, v73
	v_add_f32_e32 v17, v30, v18
	v_mfma_f32_16x16x32_bf16 v[20:23], v[244:247], v[24:27], v[20:23]
	v_mul_f32_e32 v16, v17, v16
	v_cvt_pk_bf16_f32 v16, v16, s0
	global_store_short v[62:63], v16, off offset:288
	v_add_f32_e32 v25, v34, v19
	ds_read_b128 v[16:19], v152 offset:9920
	v_mfma_f32_16x16x32_bf16 v[20:23], v[248:251], v[56:59], v[20:23]
	v_lshlrev_b32_e32 v24, 16, v76
	v_mul_f32_e32 v24, v25, v24
	v_cvt_pk_bf16_f32 v24, v24, s0
	s_waitcnt lgkmcnt(0)
	v_mfma_f32_16x16x32_bf16 v[16:19], v[252:255], v[16:19], v[20:23]
	global_store_short v[62:63], v24, off offset:416
	ds_read_b128 v[24:27], v152 offset:14144
	ds_read_b128 v[56:59], v152 offset:14208
	v_lshlrev_b32_e32 v20, 16, v68
	s_nop 3
	v_add_f32_e32 v16, v32, v16
	v_mul_f32_e32 v16, v16, v20
	ds_read_b128 v[20:23], v152 offset:14080
	v_cvt_pk_bf16_f32 v16, v16, s0
	s_waitcnt lgkmcnt(0)
	v_mfma_f32_16x16x32_bf16 v[20:23], v[240:243], v[20:23], 0
	global_store_short v[62:63], v16, off offset:64
	v_lshlrev_b32_e32 v16, 16, v71
	v_add_f32_e32 v17, v31, v17
	v_mul_f32_e32 v16, v17, v16
	v_cvt_pk_bf16_f32 v16, v16, s0
	global_store_short v[62:63], v16, off offset:192
	v_lshlrev_b32_e32 v16, 16, v74
	v_add_f32_e32 v17, v30, v18
	v_mfma_f32_16x16x32_bf16 v[20:23], v[244:247], v[24:27], v[20:23]
	v_mul_f32_e32 v16, v17, v16
	v_cvt_pk_bf16_f32 v16, v16, s0
	global_store_short v[62:63], v16, off offset:320
	v_add_f32_e32 v25, v34, v19
	ds_read_b128 v[16:19], v152 offset:14272
	v_mfma_f32_16x16x32_bf16 v[20:23], v[248:251], v[56:59], v[20:23]
	v_lshlrev_b32_e32 v24, 16, v77
	v_mul_f32_e32 v24, v25, v24
	v_cvt_pk_bf16_f32 v24, v24, s0
	s_waitcnt lgkmcnt(0)
	v_mfma_f32_16x16x32_bf16 v[16:19], v[252:255], v[16:19], v[20:23]
	global_store_short v[62:63], v24, off offset:448
	ds_read_b128 v[24:27], v152 offset:18496
	ds_read_b128 v[56:59], v152 offset:18560
	v_lshlrev_b32_e32 v20, 16, v52
	s_nop 3
	v_add_f32_e32 v16, v32, v16
	v_mul_f32_e32 v16, v16, v20
	ds_read_b128 v[20:23], v152 offset:18432
	v_cvt_pk_bf16_f32 v16, v16, s0
	s_waitcnt lgkmcnt(0)
; __device__ __forceinline__ bf16_t f2bf(float v) { return (bf16_t)(cvt_pk_bf16(v, 0.f) & 0xffffu); }
; __device__ __forceinline__ float bf2f(bf16_t b) { return __uint_as_float(((unsigned)b) << 16); }
; __device__ __forceinline__ size_t tl(int r, int c, int K) { return ((size_t)(r >> 8) * (size_t)(K >> 6) + (size_t)(c >> 6)) * 16384 + (size_t)((r & 255) << 6) + (size_t)(c & 63); }
; #define MFMA16(a, b, c) __builtin_amdgcn_mfma_f32_16x16x32_bf16((a), (b), (c), 0, 0, 0)
; __device__ __forceinline__ void gmlp_item(KP P, int ch, int h, unsigned char* lds) {
;     ...
; #pragma unroll
;         for (int db = 0; db < 8; ++db) {
;             f32x4 acc = (f32x4){0.f, 0.f, 0.f, 0.f};
; #pragma unroll
;             for (int ks = 0; ks < 4; ++ks) acc = MFMA16(Wa[ks], *(const bf16x8*)(T + (db * 16 + l15) * 136 + ks * 32 + 8 * q), acc);
; #pragma unroll
;             for (int reg = 0; reg < 4; ++reg) {
;                 const int tt = 16 * w + q * 4 + reg, c = h * 128 + db * 16 + l15;
;                 gm[tl(r0 + tt, c, 1024)] = f2bf(bf2f(uu16[db][reg]) * (acc[reg] + bsv[reg]));
;             }
;         }
;     }
;     __syncthreads();
	v_mfma_f32_16x16x32_bf16 v[20:23], v[240:243], v[20:23], 0
	global_store_short v[62:63], v16, off offset:96
	v_lshlrev_b32_e32 v16, 16, v55
	v_add_f32_e32 v17, v31, v17
	v_mul_f32_e32 v16, v17, v16
	v_cvt_pk_bf16_f32 v16, v16, s0
	global_store_short v[62:63], v16, off offset:224
	v_lshlrev_b32_e32 v16, 16, v53
	v_add_f32_e32 v17, v30, v18
	v_mfma_f32_16x16x32_bf16 v[20:23], v[244:247], v[24:27], v[20:23]
	v_mul_f32_e32 v16, v17, v16
	v_cvt_pk_bf16_f32 v16, v16, s0
	global_store_short v[62:63], v16, off offset:352
	v_add_f32_e32 v25, v34, v19
	ds_read_b128 v[16:19], v152 offset:18624
	v_mfma_f32_16x16x32_bf16 v[20:23], v[248:251], v[56:59], v[20:23]
	v_lshlrev_b32_e32 v24, 16, v54
	v_mul_f32_e32 v24, v25, v24
	v_cvt_pk_bf16_f32 v24, v24, s0
	s_waitcnt lgkmcnt(0)
	v_mfma_f32_16x16x32_bf16 v[16:19], v[252:255], v[16:19], v[20:23]
	global_store_short v[62:63], v24, off offset:480
	ds_read_b128 v[24:27], v152 offset:22848
	s_nop 0
	v_lshlrev_b32_e32 v20, 16, v49
	s_nop 3
	v_add_f32_e32 v16, v32, v16
	v_mul_f32_e32 v16, v16, v20
	v_lshl_add_u64 v[20:21], s[40:41], 0, v[102:103]
	v_lshl_add_u64 v[20:21], v[20:21], 0, v[28:29]
	v_lshl_add_u64 v[28:29], v[20:21], 0, v[60:61]
	ds_read_b128 v[20:23], v152 offset:22784
	v_cvt_pk_bf16_f32 v16, v16, s0
	s_waitcnt lgkmcnt(0)
	v_mfma_f32_16x16x32_bf16 v[20:23], v[240:243], v[20:23], 0
	global_store_short v[28:29], v16, off
	v_lshlrev_b32_e32 v16, 16, v50
	v_add_f32_e32 v17, v31, v17
	v_mul_f32_e32 v16, v17, v16
	v_cvt_pk_bf16_f32 v16, v16, s0
	ds_read_b128 v[50:53], v152 offset:22912
	global_store_short v[28:29], v16, off offset:128
	v_lshlrev_b32_e32 v16, 16, v47
	v_add_f32_e32 v17, v30, v18
	v_mfma_f32_16x16x32_bf16 v[20:23], v[244:247], v[24:27], v[20:23]
	v_mul_f32_e32 v16, v17, v16
	v_cvt_pk_bf16_f32 v16, v16, s0
	global_store_short v[28:29], v16, off offset:256
	v_add_f32_e32 v25, v34, v19
	ds_read_b128 v[16:19], v152 offset:22976
	s_waitcnt lgkmcnt(1)
	v_mfma_f32_16x16x32_bf16 v[20:23], v[248:251], v[50:53], v[20:23]
	v_lshlrev_b32_e32 v24, 16, v48
	v_mul_f32_e32 v24, v25, v24
	v_cvt_pk_bf16_f32 v24, v24, s0
	s_waitcnt lgkmcnt(0)
	v_mfma_f32_16x16x32_bf16 v[16:19], v[252:255], v[16:19], v[20:23]
	global_store_short v[28:29], v24, off offset:384
	ds_read_b128 v[24:27], v152 offset:27200
	ds_read_b128 v[46:49], v152 offset:27264
	v_lshlrev_b32_e32 v20, 16, v42
	s_nop 3
	v_add_f32_e32 v16, v32, v16
	v_mul_f32_e32 v16, v16, v20
	ds_read_b128 v[20:23], v152 offset:27136
	v_cvt_pk_bf16_f32 v16, v16, s0
	s_waitcnt lgkmcnt(0)
	v_mfma_f32_16x16x32_bf16 v[20:23], v[240:243], v[20:23], 0
	global_store_short v[28:29], v16, off offset:32
	v_lshlrev_b32_e32 v16, 16, v45
	v_add_f32_e32 v17, v31, v17
	v_mul_f32_e32 v16, v17, v16
	v_cvt_pk_bf16_f32 v16, v16, s0
	global_store_short v[28:29], v16, off offset:160
	v_lshlrev_b32_e32 v16, 16, v43
	v_add_f32_e32 v17, v30, v18
	v_mfma_f32_16x16x32_bf16 v[20:23], v[244:247], v[24:27], v[20:23]
	v_mul_f32_e32 v16, v17, v16
	v_cvt_pk_bf16_f32 v16, v16, s0
	global_store_short v[28:29], v16, off offset:288
	v_add_f32_e32 v25, v34, v19
	ds_read_b128 v[16:19], v152 offset:27328
	v_mfma_f32_16x16x32_bf16 v[20:23], v[248:251], v[46:49], v[20:23]
	v_lshlrev_b32_e32 v24, 16, v44
	v_mul_f32_e32 v24, v25, v24
	v_cvt_pk_bf16_f32 v24, v24, s0
	s_waitcnt lgkmcnt(0)
	v_mfma_f32_16x16x32_bf16 v[16:19], v[252:255], v[16:19], v[20:23]
	global_store_short v[28:29], v24, off offset:416
	ds_read_b128 v[24:27], v152 offset:31552
	s_nop 0
	v_lshlrev_b32_e32 v20, 16, v38
	s_nop 3
	v_add_f32_e32 v16, v32, v16
	v_mul_f32_e32 v16, v16, v20
	ds_read_b128 v[20:23], v152 offset:31488
	s_waitcnt lgkmcnt(0)
	v_mfma_f32_16x16x32_bf16 v[12:15], v[240:243], v[20:23], 0
	ds_read_b128 v[20:23], v152 offset:31616
	v_cvt_pk_bf16_f32 v16, v16, s0
	global_store_short v[28:29], v16, off offset:64
	v_mfma_f32_16x16x32_bf16 v[0:3], v[244:247], v[24:27], v[12:15]
	v_lshlrev_b32_e32 v16, 16, v41
	v_add_f32_e32 v17, v31, v17
	v_mul_f32_e32 v16, v17, v16
	s_nop 0
	ds_read_b128 v[12:15], v152 offset:31680
	s_waitcnt lgkmcnt(1)
	v_mfma_f32_16x16x32_bf16 v[0:3], v[248:251], v[20:23], v[0:3]
	v_cvt_pk_bf16_f32 v16, v16, s0
	global_store_short v[28:29], v16, off offset:192
	v_lshlrev_b32_e32 v16, 16, v39
	v_add_f32_e32 v17, v30, v18
	v_mul_f32_e32 v16, v17, v16
	v_cvt_pk_bf16_f32 v16, v16, s0
	s_waitcnt lgkmcnt(0)
	v_mfma_f32_16x16x32_bf16 v[0:3], v[252:255], v[12:15], v[0:3]
	global_store_short v[28:29], v16, off offset:320
	v_lshlrev_b32_e32 v16, 16, v40
	v_add_f32_e32 v17, v34, v19
	v_mul_f32_e32 v4, v17, v16
	v_cvt_pk_bf16_f32 v4, v4, s0
	global_store_short v[28:29], v4, off offset:448
	v_lshlrev_b32_e32 v4, 16, v33
	s_nop 0
	v_add_f32_e32 v0, v32, v0
	v_mul_f32_e32 v0, v0, v4
	v_cvt_pk_bf16_f32 v0, v0, s0
	global_store_short v[28:29], v0, off offset:96
	v_lshlrev_b32_e32 v0, 16, v35
	v_add_f32_e32 v1, v31, v1
	v_mul_f32_e32 v0, v1, v0
	v_cvt_pk_bf16_f32 v0, v0, s0
	global_store_short v[28:29], v0, off offset:224
	v_lshlrev_b32_e32 v0, 16, v36
	v_add_f32_e32 v1, v30, v2
	v_mul_f32_e32 v0, v1, v0
	v_cvt_pk_bf16_f32 v0, v0, s0
	global_store_short v[28:29], v0, off offset:352
	v_lshlrev_b32_e32 v0, 16, v37
	v_add_f32_e32 v1, v34, v3
	v_mul_f32_e32 v0, v1, v0
	v_cvt_pk_bf16_f32 v0, v0, s0
	global_store_short v[28:29], v0, off offset:480
	s_barrier
